# attn_sample K loops: keys 3..15 of a full pass addressed by a running 64-bit pointer (one add per key) instead of the generic 12-instruction select chain
# baseline (speedup 1.0000x reference)
; __device__ __forceinline__ void attn_sample(const Params& p, int j, LAS unsigned char* lds, int gw, int NGW, int wave, int lane) {
;     ...
;             for (int jj0 = 0; jj0 < 129; jj0 += 64) {
;                 f32x4 kv[16];
; #pragma unroll
;                 for (int u = 0; u < 16; ++u) { int jj = jj0 + u * 4 + rs; jj = jj > 128 ? 128 : jj; const int pos = W + t - (jj << dsh);
;                     kv[u] = *(const f32x4*)(pos >= W ? nbuf + (size_t)(pos - 8) * 1024 : cache + (size_t)pos * 1024); }
.LBB0_328:
	v_add_u32_e32 v79, s42, v65
	v_add_u32_e32 v78, 64, v79
	v_min_i32_e32 v0, 0x80, v78
	v_sub_u32_e32 v0, s34, v0
	v_add_u32_e32 v1, -8, v0
	v_cmp_gt_i32_e32 vcc, s78, v0
	v_mov_b32_e32 v80, 0
	s_nop 0
	v_cndmask_b32_e32 v184, v1, v0, vcc
	v_cndmask_b32_e32 v1, v77, v71, vcc
	v_cndmask_b32_e32 v0, v76, v70, vcc
	v_lshlrev_b64 v[2:3], 12, v[184:185]
	v_lshl_add_u64 v[0:1], v[0:1], 0, v[2:3]
	global_load_dwordx4 v[92:95], v[0:1], off
	s_cmp_eq_u32 s42, 64
	s_cbranch_scc1 .Las_k0_mini
	v_add_u32_e32 v0, 0x44, v79
	v_min_i32_e32 v0, 0x80, v0
	v_sub_u32_e32 v0, s34, v0
	v_add_u32_e32 v1, -8, v0
	v_cmp_gt_i32_e32 vcc, s78, v0
	s_nop 1
	v_cndmask_b32_e32 v184, v1, v0, vcc
	v_cndmask_b32_e32 v1, v77, v71, vcc
	v_cndmask_b32_e32 v0, v76, v70, vcc
	v_lshlrev_b64 v[2:3], 12, v[184:185]
	v_lshl_add_u64 v[0:1], v[0:1], 0, v[2:3]
	global_load_dwordx4 v[56:59], v[0:1], off
	v_add_u32_e32 v0, 0x48, v79
	v_min_i32_e32 v0, 0x80, v0
	v_sub_u32_e32 v0, s34, v0
	v_add_u32_e32 v1, -8, v0
	v_cmp_gt_i32_e32 vcc, s78, v0
	s_nop 1
	v_cndmask_b32_e32 v184, v1, v0, vcc
	v_cndmask_b32_e32 v1, v77, v71, vcc
	v_cndmask_b32_e32 v0, v76, v70, vcc
	v_lshlrev_b64 v[2:3], 12, v[184:185]
	v_lshl_add_u64 v[0:1], v[0:1], 0, v[2:3]
	global_load_dwordx4 v[52:55], v[0:1], off
	s_mov_b32 s100, 0xffffc000
	s_mov_b32 s101, -1
	v_lshl_add_u64 v[114:115], v[0:1], 0, s[100:101]
	global_load_dwordx4 v[48:51], v[114:115], off
	v_lshl_add_u64 v[114:115], v[114:115], 0, s[100:101]
	global_load_dwordx4 v[44:47], v[114:115], off
	v_lshl_add_u64 v[114:115], v[114:115], 0, s[100:101]
	global_load_dwordx4 v[40:43], v[114:115], off
	v_lshl_add_u64 v[114:115], v[114:115], 0, s[100:101]
	global_load_dwordx4 v[36:39], v[114:115], off
	v_lshl_add_u64 v[114:115], v[114:115], 0, s[100:101]
	global_load_dwordx4 v[32:35], v[114:115], off
	v_lshl_add_u64 v[114:115], v[114:115], 0, s[100:101]
	global_load_dwordx4 v[28:31], v[114:115], off
	v_lshl_add_u64 v[114:115], v[114:115], 0, s[100:101]
	global_load_dwordx4 v[24:27], v[114:115], off
	v_lshl_add_u64 v[114:115], v[114:115], 0, s[100:101]
	global_load_dwordx4 v[20:23], v[114:115], off
	v_lshl_add_u64 v[114:115], v[114:115], 0, s[100:101]
	global_load_dwordx4 v[16:19], v[114:115], off
	v_lshl_add_u64 v[114:115], v[114:115], 0, s[100:101]
	global_load_dwordx4 v[12:15], v[114:115], off
	v_lshl_add_u64 v[114:115], v[114:115], 0, s[100:101]
	global_load_dwordx4 v[8:11], v[114:115], off
	v_lshl_add_u64 v[114:115], v[114:115], 0, s[100:101]
	global_load_dwordx4 v[4:7], v[114:115], off
	v_lshl_add_u64 v[114:115], v[114:115], 0, s[100:101]
	s_waitcnt vmcnt(14)
	v_mul_f32_e32 v79, v63, v93
	v_fmac_f32_e32 v79, v62, v92
	global_load_dwordx4 v[0:3], v[114:115], off
	v_fmac_f32_e32 v79, v60, v94
	v_fmac_f32_e32 v79, v61, v95
	v_cmp_gt_i32_e32 vcc, s35, v78
	s_nop 0
	v_add_f32_dpp v79, v79, v79 row_ror:8 row_mask:0xf bank_mask:0xf bound_ctrl:1
	s_nop 1
	v_add_f32_dpp v79, v79, v79 row_ror:4 row_mask:0xf bank_mask:0xf bound_ctrl:1
	s_nop 1
	v_add_f32_dpp v79, v79, v79 row_ror:2 row_mask:0xf bank_mask:0xf bound_ctrl:1
	s_nop 1
	v_mov_b32_dpp v80, v79 row_ror:1 row_mask:0xf bank_mask:0xf
	s_and_saveexec_b64 s[12:13], vcc
	s_cbranch_execz .LBB0_332
	v_add_f32_e32 v79, v79, v80
	s_and_saveexec_b64 s[30:31], s[36:37]
	ds_write_b32 v69, v79
	s_or_b64 exec, exec, s[30:31]
	v_max_f32_e32 v67, v67, v67
	v_max_f32_e32 v67, v67, v79

; __device__ __forceinline__ void attn_sample(const Params& p, int j, LAS unsigned char* lds, int gw, int NGW, int wave, int lane) {
;     ...
;             for (int jj0 = 0; jj0 < 129; jj0 += 64) {
;                 f32x4 kv[16];
; #pragma unroll
;                 for (int u = 0; u < 16; ++u) { int jj = jj0 + u * 4 + rs; jj = jj > 128 ? 128 : jj; const int pos = W + t - (jj << dsh);
;                     kv[u] = *(const f32x4*)(pos >= W ? nbuf + (size_t)(pos - 8) * 1024 : cache + (size_t)pos * 1024); }
.LBB0_394:
	v_add_u32_e32 v84, s52, v65
	v_add_u32_e32 v82, 64, v84
	v_min_i32_e32 v0, 0x80, v82
	v_lshlrev_b32_e32 v0, 2, v0
	v_sub_u32_e32 v0, s46, v0
	v_ashrrev_i32_e32 v1, 31, v0
	v_add_u32_e32 v2, -8, v0
	v_cmp_gt_i32_e32 vcc, s19, v0
	s_nop 1
	v_cndmask_b32_e32 v1, 0, v1, vcc
	v_cndmask_b32_e32 v0, v2, v0, vcc
	v_cndmask_b32_e32 v3, v81, v73, vcc
	v_cndmask_b32_e32 v2, v80, v72, vcc
	v_lshlrev_b64 v[0:1], 12, v[0:1]
	v_lshl_add_u64 v[0:1], v[2:3], 0, v[0:1]
	global_load_dwordx4 v[60:63], v[0:1], off
	s_cmp_eq_u32 s52, 64
	s_cbranch_scc1 .Las_k1_mini
	v_add_u32_e32 v0, 0x44, v84
	v_min_i32_e32 v0, 0x80, v0
	v_lshlrev_b32_e32 v0, 2, v0
	v_sub_u32_e32 v0, s46, v0
	v_ashrrev_i32_e32 v1, 31, v0
	v_add_u32_e32 v2, -8, v0
	v_cmp_gt_i32_e32 vcc, s19, v0
	s_waitcnt vmcnt(0)
	v_mul_f32_e32 v61, v79, v61
	v_cndmask_b32_e32 v1, 0, v1, vcc
	v_cndmask_b32_e32 v0, v2, v0, vcc
	v_cndmask_b32_e32 v3, v81, v73, vcc
	v_cndmask_b32_e32 v2, v80, v72, vcc
	v_lshlrev_b64 v[0:1], 12, v[0:1]
	v_lshl_add_u64 v[0:1], v[2:3], 0, v[0:1]
	global_load_dwordx4 v[56:59], v[0:1], off
	v_add_u32_e32 v0, 0x48, v84
	v_min_i32_e32 v0, 0x80, v0
	v_lshlrev_b32_e32 v0, 2, v0
	v_sub_u32_e32 v0, s46, v0
	v_ashrrev_i32_e32 v1, 31, v0
	v_add_u32_e32 v2, -8, v0
	v_cmp_gt_i32_e32 vcc, s19, v0
	v_fmac_f32_e32 v61, v78, v60
	v_fmac_f32_e32 v61, v76, v62
	v_cndmask_b32_e32 v1, 0, v1, vcc
	v_cndmask_b32_e32 v0, v2, v0, vcc
	v_cndmask_b32_e32 v3, v81, v73, vcc
	v_cndmask_b32_e32 v2, v80, v72, vcc
	v_lshlrev_b64 v[0:1], 12, v[0:1]
	v_lshl_add_u64 v[0:1], v[2:3], 0, v[0:1]
	global_load_dwordx4 v[52:55], v[0:1], off
	s_mov_b32 s100, 0xffff0000
	s_mov_b32 s101, -1
	v_lshl_add_u64 v[114:115], v[0:1], 0, s[100:101]
	v_fmac_f32_e32 v61, v77, v63
	global_load_dwordx4 v[48:51], v[114:115], off
	v_lshl_add_u64 v[114:115], v[114:115], 0, s[100:101]
	s_nop 1
	v_add_f32_dpp v60, v61, v61 row_ror:8 row_mask:0xf bank_mask:0xf bound_ctrl:1
	v_mov_b32_e32 v61, 0
	global_load_dwordx4 v[44:47], v[114:115], off
	v_lshl_add_u64 v[114:115], v[114:115], 0, s[100:101]
	s_nop 1
	v_add_f32_dpp v60, v60, v60 row_ror:4 row_mask:0xf bank_mask:0xf bound_ctrl:1
	global_load_dwordx4 v[40:43], v[114:115], off
	v_lshl_add_u64 v[114:115], v[114:115], 0, s[100:101]
	s_nop 1
	v_add_f32_dpp v60, v60, v60 row_ror:2 row_mask:0xf bank_mask:0xf bound_ctrl:1
	global_load_dwordx4 v[36:39], v[114:115], off
	v_lshl_add_u64 v[114:115], v[114:115], 0, s[100:101]
	s_nop 1
	v_mov_b32_dpp v61, v60 row_ror:1 row_mask:0xf bank_mask:0xf
	global_load_dwordx4 v[32:35], v[114:115], off
	v_lshl_add_u64 v[114:115], v[114:115], 0, s[100:101]
	global_load_dwordx4 v[28:31], v[114:115], off
	v_lshl_add_u64 v[114:115], v[114:115], 0, s[100:101]
	global_load_dwordx4 v[24:27], v[114:115], off
	v_lshl_add_u64 v[114:115], v[114:115], 0, s[100:101]
	global_load_dwordx4 v[20:23], v[114:115], off
	v_lshl_add_u64 v[114:115], v[114:115], 0, s[100:101]
	global_load_dwordx4 v[16:19], v[114:115], off
	v_lshl_add_u64 v[114:115], v[114:115], 0, s[100:101]
	global_load_dwordx4 v[12:15], v[114:115], off
	v_lshl_add_u64 v[114:115], v[114:115], 0, s[100:101]
	global_load_dwordx4 v[8:11], v[114:115], off
	v_lshl_add_u64 v[114:115], v[114:115], 0, s[100:101]
	global_load_dwordx4 v[4:7], v[114:115], off
	v_lshl_add_u64 v[114:115], v[114:115], 0, s[100:101]
	global_load_dwordx4 v[0:3], v[114:115], off
	v_cmp_gt_i32_e32 vcc, s35, v82
	s_and_saveexec_b64 s[30:31], vcc
	s_cbranch_execz .LBB0_398
	v_add_f32_e32 v60, v60, v61
	s_and_saveexec_b64 s[42:43], s[36:37]
	ds_write_b32 v69, v60
	s_or_b64 exec, exec, s[42:43]
	v_max_f32_e32 v61, v67, v67
	v_max_f32_e32 v67, v61, v60

; __device__ __forceinline__ void attn_sample(const Params& p, int j, LAS unsigned char* lds, int gw, int NGW, int wave, int lane) {
;     ...
;             for (int jj0 = 0; jj0 < 129; jj0 += 64) {
;                 f32x4 kv[16];
; #pragma unroll
;                 for (int u = 0; u < 16; ++u) { int jj = jj0 + u * 4 + rs; jj = jj > 128 ? 128 : jj; const int pos = W + t - (jj << dsh);
;                     kv[u] = *(const f32x4*)(pos >= W ? nbuf + (size_t)(pos - 8) * 1024 : cache + (size_t)pos * 1024); }
.LBB0_460:
	v_add_u32_e32 v84, s42, v65
	v_add_u32_e32 v82, 64, v84
	v_min_i32_e32 v0, 0x80, v82
	v_lshlrev_b32_e32 v0, 4, v0
	v_sub_u32_e32 v0, s47, v0
	v_ashrrev_i32_e32 v1, 31, v0
	v_add_u32_e32 v2, -8, v0
	v_cmp_gt_i32_e32 vcc, s81, v0
	s_nop 1
	v_cndmask_b32_e32 v1, 0, v1, vcc
	v_cndmask_b32_e32 v0, v2, v0, vcc
	v_cndmask_b32_e32 v3, v81, v75, vcc
	v_cndmask_b32_e32 v2, v80, v74, vcc
	v_lshlrev_b64 v[0:1], 12, v[0:1]
	v_lshl_add_u64 v[0:1], v[2:3], 0, v[0:1]
	global_load_dwordx4 v[60:63], v[0:1], off
	s_cmp_eq_u32 s42, 64
	s_cbranch_scc1 .Las_k2_mini
	v_add_u32_e32 v0, 0x44, v84
	v_min_i32_e32 v0, 0x80, v0
	v_lshlrev_b32_e32 v0, 4, v0
	v_sub_u32_e32 v0, s47, v0
	v_ashrrev_i32_e32 v1, 31, v0
	v_add_u32_e32 v2, -8, v0
	v_cmp_gt_i32_e32 vcc, s81, v0
	s_waitcnt vmcnt(0)
	v_mul_f32_e32 v61, v79, v61
	v_cndmask_b32_e32 v1, 0, v1, vcc
	v_cndmask_b32_e32 v0, v2, v0, vcc
	v_cndmask_b32_e32 v3, v81, v75, vcc
	v_cndmask_b32_e32 v2, v80, v74, vcc
	v_lshlrev_b64 v[0:1], 12, v[0:1]
	v_lshl_add_u64 v[0:1], v[2:3], 0, v[0:1]
	global_load_dwordx4 v[56:59], v[0:1], off
	v_add_u32_e32 v0, 0x48, v84
	v_min_i32_e32 v0, 0x80, v0
	v_lshlrev_b32_e32 v0, 4, v0
	v_sub_u32_e32 v0, s47, v0
	v_ashrrev_i32_e32 v1, 31, v0
	v_add_u32_e32 v2, -8, v0
	v_cmp_gt_i32_e32 vcc, s81, v0
	v_fmac_f32_e32 v61, v78, v60
	v_fmac_f32_e32 v61, v76, v62
	v_cndmask_b32_e32 v1, 0, v1, vcc
	v_cndmask_b32_e32 v0, v2, v0, vcc
	v_cndmask_b32_e32 v3, v81, v75, vcc
	v_cndmask_b32_e32 v2, v80, v74, vcc
	v_lshlrev_b64 v[0:1], 12, v[0:1]
	v_lshl_add_u64 v[0:1], v[2:3], 0, v[0:1]
	global_load_dwordx4 v[52:55], v[0:1], off
	s_mov_b32 s100, 0xfffc0000
	s_mov_b32 s101, -1
	v_lshl_add_u64 v[114:115], v[0:1], 0, s[100:101]
	v_fmac_f32_e32 v61, v77, v63
	global_load_dwordx4 v[48:51], v[114:115], off
	v_lshl_add_u64 v[114:115], v[114:115], 0, s[100:101]
	s_nop 1
	v_add_f32_dpp v60, v61, v61 row_ror:8 row_mask:0xf bank_mask:0xf bound_ctrl:1
	v_mov_b32_e32 v61, 0
	global_load_dwordx4 v[44:47], v[114:115], off
	v_lshl_add_u64 v[114:115], v[114:115], 0, s[100:101]
	s_nop 1
	v_add_f32_dpp v60, v60, v60 row_ror:4 row_mask:0xf bank_mask:0xf bound_ctrl:1
	global_load_dwordx4 v[40:43], v[114:115], off
	v_lshl_add_u64 v[114:115], v[114:115], 0, s[100:101]
	s_nop 1
	v_add_f32_dpp v60, v60, v60 row_ror:2 row_mask:0xf bank_mask:0xf bound_ctrl:1
	global_load_dwordx4 v[36:39], v[114:115], off
	v_lshl_add_u64 v[114:115], v[114:115], 0, s[100:101]
	s_nop 1
	v_mov_b32_dpp v61, v60 row_ror:1 row_mask:0xf bank_mask:0xf
	global_load_dwordx4 v[32:35], v[114:115], off
	v_lshl_add_u64 v[114:115], v[114:115], 0, s[100:101]
	global_load_dwordx4 v[28:31], v[114:115], off
	v_lshl_add_u64 v[114:115], v[114:115], 0, s[100:101]
	global_load_dwordx4 v[24:27], v[114:115], off
	v_lshl_add_u64 v[114:115], v[114:115], 0, s[100:101]
	global_load_dwordx4 v[20:23], v[114:115], off
	v_lshl_add_u64 v[114:115], v[114:115], 0, s[100:101]
	global_load_dwordx4 v[16:19], v[114:115], off
	v_lshl_add_u64 v[114:115], v[114:115], 0, s[100:101]
	global_load_dwordx4 v[12:15], v[114:115], off
	v_lshl_add_u64 v[114:115], v[114:115], 0, s[100:101]
	global_load_dwordx4 v[8:11], v[114:115], off
	v_lshl_add_u64 v[114:115], v[114:115], 0, s[100:101]
	global_load_dwordx4 v[4:7], v[114:115], off
	v_lshl_add_u64 v[114:115], v[114:115], 0, s[100:101]
	global_load_dwordx4 v[0:3], v[114:115], off
	v_cmp_gt_i32_e32 vcc, s35, v82
	s_and_saveexec_b64 s[24:25], vcc
	s_cbranch_execz .LBB0_464
	v_add_f32_e32 v60, v60, v61
	s_and_saveexec_b64 s[30:31], s[36:37]
	ds_write_b32 v69, v60
	s_or_b64 exec, exec, s[30:31]
	v_max_f32_e32 v61, v67, v67
	v_max_f32_e32 v67, v61, v60
